# GU epilogue ACT stores write-through (sc1) so the barrier writeback finds less dirty data
# speedup vs baseline: 1.0015x; 1.0015x over previous
; __device__ __forceinline__ unsigned pk2(float lo, float hi) { unsigned r; asm("v_cvt_pk_bf16_f32 %0, %1, %2" : "=v"(r) : "v"(lo), "v"(hi)); return r; }
; __device__ __forceinline__ float silu_f(float x) { return x * sigmoid_f(x); }
;     __device__ __forceinline__ void operator()(const f32x4 (&acc)[2][2][4][2], const pg8::Unit& u, int wr, int wc, int fr, int fq) const {
;     ...
;             for (int m = 0; m < 4; ++m) rs[ai][m] = ss[row0 + ai * 128 + m * 16];
; #pragma unroll
;         for (int ai = 0; ai < 2; ++ai)
; #pragma unroll
;             for (int m = 0; m < 4; ++m) {
;                 const int r = row0 + ai * 128 + m * 16;
;                 const float rstd = __builtin_amdgcn_rsqf(rs[ai][m] * (1.0f / D) + EPS);
;                 float o[8];
; #pragma unroll
;                 for (int n = 0; n < 2; ++n)
; #pragma unroll
;                     for (int e = 0; e < 4; ++e) { const float g = acc[ai][0][m][n][e] * rstd, up = acc[ai][1][m][n][e] * rstd; o[4 * n + e] = silu_f(g) * up; }
;                 u32x4 w; w.x = pk2(o[0], o[1]); w.y = pk2(o[2], o[3]); w.z = pk2(o[4], o[5]); w.w = pk2(o[6], o[7]);
;                 *(u32x4*)(ACT + (size_t)r * FF + col0) = w;
.LBB0_526:
	s_lshl_b32 s2, s45, 8
	s_add_i32 s2, s2, s39
	v_add_u32_e32 v140, s2, v145
	v_lshlrev_b32_e32 v141, 2, v140
	global_load_dword v150, v141, s[12:13]
	global_load_dword v152, v141, s[12:13] offset:64
	global_load_dword v154, v141, s[12:13] offset:128
	global_load_dword v156, v141, s[12:13] offset:192
	global_load_dword v158, v141, s[12:13] offset:512
	global_load_dword v160, v141, s[12:13] offset:576
	global_load_dword v144, v141, s[12:13] offset:640
	global_load_dword v174, v141, s[12:13] offset:704
	s_lshl_b32 s2, s44, 7
	s_or_b32 s2, s2, s40
	v_lshl_add_u32 v142, v146, 3, s2
	s_movk_i32 s17, 0x1600
	v_mul_lo_u32 v171, v140, s17
	v_lshl_add_u32 v171, v142, 1, v171
	s_mov_b32 s2, 0xbfb8aa3b
	s_waitcnt vmcnt(0)
	v_fmamk_f32 v150, v150, 0x3a800000, v199
	v_fmamk_f32 v152, v152, 0x3a800000, v199
	v_fmamk_f32 v154, v154, 0x3a800000, v199
	v_fmamk_f32 v156, v156, 0x3a800000, v199
	v_fmamk_f32 v158, v158, 0x3a800000, v199
	v_fmamk_f32 v160, v160, 0x3a800000, v199
	v_fmamk_f32 v144, v144, 0x3a800000, v199
	v_fmamk_f32 v174, v174, 0x3a800000, v199
	v_rsq_f32_e32 v150, v150
	v_rsq_f32_e32 v152, v152
	v_rsq_f32_e32 v154, v154
	v_rsq_f32_e32 v156, v156
	v_rsq_f32_e32 v158, v158
	v_rsq_f32_e32 v160, v160
	v_rsq_f32_e32 v144, v144
	v_rsq_f32_e32 v174, v174
	v_pk_mul_f32 v[124:125], v[124:125], v[150:151] op_sel_hi:[1,0]
	v_pk_mul_f32 v[120:121], v[120:121], v[150:151] op_sel_hi:[1,0]
	v_pk_mul_f32 v[126:127], v[126:127], v[150:151] op_sel_hi:[1,0]
	v_pk_mul_f32 v[122:123], v[122:123], v[150:151] op_sel_hi:[1,0]
	v_pk_mul_f32 v[140:141], v[124:125], s[2:3] op_sel_hi:[1,0]
	v_pk_mul_f32 v[142:143], v[126:127], s[2:3] op_sel_hi:[1,0]
	v_exp_f32_e32 v140, v140
	v_exp_f32_e32 v141, v141
	v_exp_f32_e32 v142, v142
	v_exp_f32_e32 v143, v143
	v_pk_add_f32 v[140:141], v[140:141], 1.0 op_sel_hi:[1,0]
	v_pk_add_f32 v[142:143], v[142:143], 1.0 op_sel_hi:[1,0]
	v_rcp_f32_e32 v140, v140
	v_rcp_f32_e32 v141, v141
	v_rcp_f32_e32 v142, v142
	v_rcp_f32_e32 v143, v143
	v_pk_mul_f32 v[124:125], v[124:125], v[140:141]
	v_pk_mul_f32 v[126:127], v[126:127], v[142:143]
	v_pk_mul_f32 v[124:125], v[124:125], v[120:121]
	v_pk_mul_f32 v[126:127], v[126:127], v[122:123]
	v_pk_mul_f32 v[116:117], v[116:117], v[150:151] op_sel_hi:[1,0]
	v_pk_mul_f32 v[112:113], v[112:113], v[150:151] op_sel_hi:[1,0]
	v_pk_mul_f32 v[118:119], v[118:119], v[150:151] op_sel_hi:[1,0]
	v_pk_mul_f32 v[114:115], v[114:115], v[150:151] op_sel_hi:[1,0]
	v_pk_mul_f32 v[140:141], v[116:117], s[2:3] op_sel_hi:[1,0]
	v_pk_mul_f32 v[142:143], v[118:119], s[2:3] op_sel_hi:[1,0]
	v_exp_f32_e32 v140, v140
	v_exp_f32_e32 v141, v141
	v_exp_f32_e32 v142, v142
	v_exp_f32_e32 v143, v143
	v_pk_add_f32 v[140:141], v[140:141], 1.0 op_sel_hi:[1,0]
	v_pk_add_f32 v[142:143], v[142:143], 1.0 op_sel_hi:[1,0]
	v_rcp_f32_e32 v140, v140
	v_rcp_f32_e32 v141, v141
	v_rcp_f32_e32 v142, v142
	v_rcp_f32_e32 v143, v143
	v_pk_mul_f32 v[116:117], v[116:117], v[140:141]
	v_pk_mul_f32 v[118:119], v[118:119], v[142:143]
	v_pk_mul_f32 v[116:117], v[116:117], v[112:113]
	v_pk_mul_f32 v[118:119], v[118:119], v[114:115]
	v_cvt_pk_bf16_f32 v124, v124, v125
	v_cvt_pk_bf16_f32 v125, v126, v127
	v_cvt_pk_bf16_f32 v126, v116, v117
	v_cvt_pk_bf16_f32 v127, v118, v119
	global_store_dwordx4 v171, v[124:127], s[10:11] sc1
	v_pk_mul_f32 v[108:109], v[108:109], v[152:153] op_sel_hi:[1,0]
	v_pk_mul_f32 v[104:105], v[104:105], v[152:153] op_sel_hi:[1,0]
	v_pk_mul_f32 v[110:111], v[110:111], v[152:153] op_sel_hi:[1,0]
	v_pk_mul_f32 v[106:107], v[106:107], v[152:153] op_sel_hi:[1,0]
	v_pk_mul_f32 v[140:141], v[108:109], s[2:3] op_sel_hi:[1,0]
	v_pk_mul_f32 v[142:143], v[110:111], s[2:3] op_sel_hi:[1,0]
	v_exp_f32_e32 v140, v140
	v_exp_f32_e32 v141, v141
	v_exp_f32_e32 v142, v142
	v_exp_f32_e32 v143, v143
	v_pk_add_f32 v[140:141], v[140:141], 1.0 op_sel_hi:[1,0]
	v_pk_add_f32 v[142:143], v[142:143], 1.0 op_sel_hi:[1,0]
	v_rcp_f32_e32 v140, v140
	v_rcp_f32_e32 v141, v141
	v_rcp_f32_e32 v142, v142
	v_rcp_f32_e32 v143, v143
	v_pk_mul_f32 v[108:109], v[108:109], v[140:141]
	v_pk_mul_f32 v[110:111], v[110:111], v[142:143]
	v_pk_mul_f32 v[108:109], v[108:109], v[104:105]
	v_pk_mul_f32 v[110:111], v[110:111], v[106:107]
	v_pk_mul_f32 v[100:101], v[100:101], v[152:153] op_sel_hi:[1,0]
	v_pk_mul_f32 v[96:97], v[96:97], v[152:153] op_sel_hi:[1,0]
	v_pk_mul_f32 v[102:103], v[102:103], v[152:153] op_sel_hi:[1,0]
	v_pk_mul_f32 v[98:99], v[98:99], v[152:153] op_sel_hi:[1,0]
	v_pk_mul_f32 v[140:141], v[100:101], s[2:3] op_sel_hi:[1,0]
	v_pk_mul_f32 v[142:143], v[102:103], s[2:3] op_sel_hi:[1,0]
	v_exp_f32_e32 v140, v140
	v_exp_f32_e32 v141, v141
	v_exp_f32_e32 v142, v142
	v_exp_f32_e32 v143, v143
	v_pk_add_f32 v[140:141], v[140:141], 1.0 op_sel_hi:[1,0]
	v_pk_add_f32 v[142:143], v[142:143], 1.0 op_sel_hi:[1,0]
	v_rcp_f32_e32 v140, v140
	v_rcp_f32_e32 v141, v141
	v_rcp_f32_e32 v142, v142
	v_rcp_f32_e32 v143, v143
	v_pk_mul_f32 v[100:101], v[100:101], v[140:141]
	v_pk_mul_f32 v[102:103], v[102:103], v[142:143]
	v_pk_mul_f32 v[100:101], v[100:101], v[96:97]
	v_pk_mul_f32 v[102:103], v[102:103], v[98:99]
	v_cvt_pk_bf16_f32 v108, v108, v109
	v_cvt_pk_bf16_f32 v109, v110, v111
	v_cvt_pk_bf16_f32 v110, v100, v101
	v_cvt_pk_bf16_f32 v111, v102, v103
	v_add_u32_e32 v149, 0x16000, v171
	global_store_dwordx4 v149, v[108:111], s[10:11] sc1
	v_pk_mul_f32 v[92:93], v[92:93], v[154:155] op_sel_hi:[1,0]
	v_pk_mul_f32 v[88:89], v[88:89], v[154:155] op_sel_hi:[1,0]
	v_pk_mul_f32 v[94:95], v[94:95], v[154:155] op_sel_hi:[1,0]
	v_pk_mul_f32 v[90:91], v[90:91], v[154:155] op_sel_hi:[1,0]
	v_pk_mul_f32 v[140:141], v[92:93], s[2:3] op_sel_hi:[1,0]
	v_pk_mul_f32 v[142:143], v[94:95], s[2:3] op_sel_hi:[1,0]
; __device__ __forceinline__ unsigned pk2(float lo, float hi) { unsigned r; asm("v_cvt_pk_bf16_f32 %0, %1, %2" : "=v"(r) : "v"(lo), "v"(hi)); return r; }
; __device__ __forceinline__ float silu_f(float x) { return x * sigmoid_f(x); }
;     __device__ __forceinline__ void operator()(const f32x4 (&acc)[2][2][4][2], const pg8::Unit& u, int wr, int wc, int fr, int fq) const {
;     ...
;         for (int ai = 0; ai < 2; ++ai)
; #pragma unroll
;             for (int m = 0; m < 4; ++m) {
;                 const int r = row0 + ai * 128 + m * 16;
;                 const float rstd = __builtin_amdgcn_rsqf(rs[ai][m] * (1.0f / D) + EPS);
;                 float o[8];
; #pragma unroll
;                 for (int n = 0; n < 2; ++n)
; #pragma unroll
;                     for (int e = 0; e < 4; ++e) { const float g = acc[ai][0][m][n][e] * rstd, up = acc[ai][1][m][n][e] * rstd; o[4 * n + e] = silu_f(g) * up; }
;                 u32x4 w; w.x = pk2(o[0], o[1]); w.y = pk2(o[2], o[3]); w.z = pk2(o[4], o[5]); w.w = pk2(o[6], o[7]);
;                 *(u32x4*)(ACT + (size_t)r * FF + col0) = w;
	v_exp_f32_e32 v140, v140
	v_exp_f32_e32 v141, v141
	v_exp_f32_e32 v142, v142
	v_exp_f32_e32 v143, v143
	v_pk_add_f32 v[140:141], v[140:141], 1.0 op_sel_hi:[1,0]
	v_pk_add_f32 v[142:143], v[142:143], 1.0 op_sel_hi:[1,0]
	v_rcp_f32_e32 v140, v140
	v_rcp_f32_e32 v141, v141
	v_rcp_f32_e32 v142, v142
	v_rcp_f32_e32 v143, v143
	v_pk_mul_f32 v[92:93], v[92:93], v[140:141]
	v_pk_mul_f32 v[94:95], v[94:95], v[142:143]
	v_pk_mul_f32 v[92:93], v[92:93], v[88:89]
	v_pk_mul_f32 v[94:95], v[94:95], v[90:91]
	v_pk_mul_f32 v[84:85], v[84:85], v[154:155] op_sel_hi:[1,0]
	v_pk_mul_f32 v[80:81], v[80:81], v[154:155] op_sel_hi:[1,0]
	v_pk_mul_f32 v[86:87], v[86:87], v[154:155] op_sel_hi:[1,0]
	v_pk_mul_f32 v[82:83], v[82:83], v[154:155] op_sel_hi:[1,0]
	v_pk_mul_f32 v[140:141], v[84:85], s[2:3] op_sel_hi:[1,0]
	v_pk_mul_f32 v[142:143], v[86:87], s[2:3] op_sel_hi:[1,0]
	v_exp_f32_e32 v140, v140
	v_exp_f32_e32 v141, v141
	v_exp_f32_e32 v142, v142
	v_exp_f32_e32 v143, v143
	v_pk_add_f32 v[140:141], v[140:141], 1.0 op_sel_hi:[1,0]
	v_pk_add_f32 v[142:143], v[142:143], 1.0 op_sel_hi:[1,0]
	v_rcp_f32_e32 v140, v140
	v_rcp_f32_e32 v141, v141
	v_rcp_f32_e32 v142, v142
	v_rcp_f32_e32 v143, v143
	v_pk_mul_f32 v[84:85], v[84:85], v[140:141]
	v_pk_mul_f32 v[86:87], v[86:87], v[142:143]
	v_pk_mul_f32 v[84:85], v[84:85], v[80:81]
	v_pk_mul_f32 v[86:87], v[86:87], v[82:83]
	v_cvt_pk_bf16_f32 v92, v92, v93
	v_cvt_pk_bf16_f32 v93, v94, v95
	v_cvt_pk_bf16_f32 v94, v84, v85
	v_cvt_pk_bf16_f32 v95, v86, v87
	v_add_u32_e32 v149, 0x2c000, v171
	global_store_dwordx4 v149, v[92:95], s[10:11] sc1
	v_pk_mul_f32 v[76:77], v[76:77], v[156:157] op_sel_hi:[1,0]
	v_pk_mul_f32 v[72:73], v[72:73], v[156:157] op_sel_hi:[1,0]
	v_pk_mul_f32 v[78:79], v[78:79], v[156:157] op_sel_hi:[1,0]
	v_pk_mul_f32 v[74:75], v[74:75], v[156:157] op_sel_hi:[1,0]
	v_pk_mul_f32 v[140:141], v[76:77], s[2:3] op_sel_hi:[1,0]
	v_pk_mul_f32 v[142:143], v[78:79], s[2:3] op_sel_hi:[1,0]
	v_exp_f32_e32 v140, v140
	v_exp_f32_e32 v141, v141
	v_exp_f32_e32 v142, v142
	v_exp_f32_e32 v143, v143
	v_pk_add_f32 v[140:141], v[140:141], 1.0 op_sel_hi:[1,0]
	v_pk_add_f32 v[142:143], v[142:143], 1.0 op_sel_hi:[1,0]
	v_rcp_f32_e32 v140, v140
	v_rcp_f32_e32 v141, v141
	v_rcp_f32_e32 v142, v142
	v_rcp_f32_e32 v143, v143
	v_pk_mul_f32 v[76:77], v[76:77], v[140:141]
	v_pk_mul_f32 v[78:79], v[78:79], v[142:143]
	v_pk_mul_f32 v[76:77], v[76:77], v[72:73]
	v_pk_mul_f32 v[78:79], v[78:79], v[74:75]
	v_pk_mul_f32 v[68:69], v[68:69], v[156:157] op_sel_hi:[1,0]
	v_pk_mul_f32 v[64:65], v[64:65], v[156:157] op_sel_hi:[1,0]
	v_pk_mul_f32 v[70:71], v[70:71], v[156:157] op_sel_hi:[1,0]
	v_pk_mul_f32 v[66:67], v[66:67], v[156:157] op_sel_hi:[1,0]
	v_pk_mul_f32 v[140:141], v[68:69], s[2:3] op_sel_hi:[1,0]
	v_pk_mul_f32 v[142:143], v[70:71], s[2:3] op_sel_hi:[1,0]
	v_exp_f32_e32 v140, v140
	v_exp_f32_e32 v141, v141
	v_exp_f32_e32 v142, v142
	v_exp_f32_e32 v143, v143
	v_pk_add_f32 v[140:141], v[140:141], 1.0 op_sel_hi:[1,0]
	v_pk_add_f32 v[142:143], v[142:143], 1.0 op_sel_hi:[1,0]
	v_rcp_f32_e32 v140, v140
	v_rcp_f32_e32 v141, v141
	v_rcp_f32_e32 v142, v142
	v_rcp_f32_e32 v143, v143
	v_pk_mul_f32 v[68:69], v[68:69], v[140:141]
	v_pk_mul_f32 v[70:71], v[70:71], v[142:143]
	v_pk_mul_f32 v[68:69], v[68:69], v[64:65]
	v_pk_mul_f32 v[70:71], v[70:71], v[66:67]
	v_cvt_pk_bf16_f32 v76, v76, v77
	v_cvt_pk_bf16_f32 v77, v78, v79
	v_cvt_pk_bf16_f32 v78, v68, v69
	v_cvt_pk_bf16_f32 v79, v70, v71
	v_add_u32_e32 v149, 0x42000, v171
	global_store_dwordx4 v149, v[76:79], s[10:11] sc1
	v_pk_mul_f32 v[60:61], v[60:61], v[158:159] op_sel_hi:[1,0]
	v_pk_mul_f32 v[56:57], v[56:57], v[158:159] op_sel_hi:[1,0]
	v_pk_mul_f32 v[62:63], v[62:63], v[158:159] op_sel_hi:[1,0]
	v_pk_mul_f32 v[58:59], v[58:59], v[158:159] op_sel_hi:[1,0]
	v_pk_mul_f32 v[140:141], v[60:61], s[2:3] op_sel_hi:[1,0]
	v_pk_mul_f32 v[142:143], v[62:63], s[2:3] op_sel_hi:[1,0]
	v_exp_f32_e32 v140, v140
	v_exp_f32_e32 v141, v141
	v_exp_f32_e32 v142, v142
	v_exp_f32_e32 v143, v143
	v_pk_add_f32 v[140:141], v[140:141], 1.0 op_sel_hi:[1,0]
	v_pk_add_f32 v[142:143], v[142:143], 1.0 op_sel_hi:[1,0]
	v_rcp_f32_e32 v140, v140
	v_rcp_f32_e32 v141, v141
	v_rcp_f32_e32 v142, v142
	v_rcp_f32_e32 v143, v143
	v_pk_mul_f32 v[60:61], v[60:61], v[140:141]
	v_pk_mul_f32 v[62:63], v[62:63], v[142:143]
	v_pk_mul_f32 v[60:61], v[60:61], v[56:57]
	v_pk_mul_f32 v[62:63], v[62:63], v[58:59]
	v_pk_mul_f32 v[52:53], v[52:53], v[158:159] op_sel_hi:[1,0]
	v_pk_mul_f32 v[48:49], v[48:49], v[158:159] op_sel_hi:[1,0]
	v_pk_mul_f32 v[54:55], v[54:55], v[158:159] op_sel_hi:[1,0]
	v_pk_mul_f32 v[50:51], v[50:51], v[158:159] op_sel_hi:[1,0]
	v_pk_mul_f32 v[140:141], v[52:53], s[2:3] op_sel_hi:[1,0]
	v_pk_mul_f32 v[142:143], v[54:55], s[2:3] op_sel_hi:[1,0]
	v_exp_f32_e32 v140, v140
	v_exp_f32_e32 v141, v141
	v_exp_f32_e32 v142, v142
	v_exp_f32_e32 v143, v143
	v_pk_add_f32 v[140:141], v[140:141], 1.0 op_sel_hi:[1,0]
	v_pk_add_f32 v[142:143], v[142:143], 1.0 op_sel_hi:[1,0]
	v_rcp_f32_e32 v140, v140
	v_rcp_f32_e32 v141, v141
	v_rcp_f32_e32 v142, v142
	v_rcp_f32_e32 v143, v143
	v_pk_mul_f32 v[52:53], v[52:53], v[140:141]
	v_pk_mul_f32 v[54:55], v[54:55], v[142:143]
	v_pk_mul_f32 v[52:53], v[52:53], v[48:49]
	v_pk_mul_f32 v[54:55], v[54:55], v[50:51]
	v_cvt_pk_bf16_f32 v60, v60, v61
	v_cvt_pk_bf16_f32 v61, v62, v63
	v_cvt_pk_bf16_f32 v62, v52, v53
	v_cvt_pk_bf16_f32 v63, v54, v55
	v_add_u32_e32 v149, 0xb0000, v171
	global_store_dwordx4 v149, v[60:63], s[10:11] sc1
	v_pk_mul_f32 v[44:45], v[44:45], v[160:161] op_sel_hi:[1,0]
	v_pk_mul_f32 v[40:41], v[40:41], v[160:161] op_sel_hi:[1,0]
	v_pk_mul_f32 v[46:47], v[46:47], v[160:161] op_sel_hi:[1,0]
; #define PG8_BAR __builtin_amdgcn_s_barrier()
; #define PG8_ZERO_ACC() do { _Pragma("unroll") for (int a = 0; a < 2; ++a) _Pragma("unroll") for (int b = 0; b < 2; ++b) _Pragma("unroll") for (int m = 0; m < 4; ++m) _Pragma("unroll") for (int n = 0; n < 2; ++n) acc[a][b][m][n] = (f32x4){0.f, 0.f, 0.f, 0.f}; } while (0)
; __device__ __forceinline__ unsigned pk2(float lo, float hi) { unsigned r; asm("v_cvt_pk_bf16_f32 %0, %1, %2" : "=v"(r) : "v"(lo), "v"(hi)); return r; }
; __device__ __forceinline__ float silu_f(float x) { return x * sigmoid_f(x); }
; template <class Epi, class Sched, bool ALIGN_EPI = false, bool SP2 = false>
; __device__ __forceinline__ void gemm_phase(PG8_LAS unsigned char* lds, const Gemm g, const Sched& S, const Epi& E, const int wave_s) {
;     ...
;         if (!has_next) break;
;     ...
;         if constexpr (Epi::INIT_ACC) {
;             if (Sched::STREAMK && nxt.kind == 2) S.load_partial(acc, tid, wid, lane);
;             else if (nxt.kind == 0) { int fr_i = fr, fq_i = fq; asm volatile("" : "+v"(fr_i), "+v"(fq_i)); E.init(acc, nxt, wr, wc, fr_i, fq_i); }
;             else PG8_ZERO_ACC();
;         } else {
;             if (Sched::STREAMK && nxt.kind == 2) S.load_partial(acc, tid, wid, lane);
;             else PG8_ZERO_ACC();
;         }
;     ...
;         cur = nxt; cA = nA; cB = nB; ++ui;
;         if constexpr (ALIGN_EPI) { if (wr == 1) PG8_BAR; }
;     __device__ __forceinline__ void operator()(const f32x4 (&acc)[2][2][4][2], const pg8::Unit& u, int wr, int wc, int fr, int fq) const {
;     ...
;         for (int ai = 0; ai < 2; ++ai)
; #pragma unroll
;             for (int m = 0; m < 4; ++m) {
;                 const int r = row0 + ai * 128 + m * 16;
;                 const float rstd = __builtin_amdgcn_rsqf(rs[ai][m] * (1.0f / D) + EPS);
;                 float o[8];
; #pragma unroll
;                 for (int n = 0; n < 2; ++n)
; #pragma unroll
;                     for (int e = 0; e < 4; ++e) { const float g = acc[ai][0][m][n][e] * rstd, up = acc[ai][1][m][n][e] * rstd; o[4 * n + e] = silu_f(g) * up; }
;                 u32x4 w; w.x = pk2(o[0], o[1]); w.y = pk2(o[2], o[3]); w.z = pk2(o[4], o[5]); w.w = pk2(o[6], o[7]);
;                 *(u32x4*)(ACT + (size_t)r * FF + col0) = w;
	v_pk_mul_f32 v[42:43], v[42:43], v[160:161] op_sel_hi:[1,0]
	v_pk_mul_f32 v[140:141], v[44:45], s[2:3] op_sel_hi:[1,0]
	v_pk_mul_f32 v[142:143], v[46:47], s[2:3] op_sel_hi:[1,0]
	v_exp_f32_e32 v140, v140
	v_exp_f32_e32 v141, v141
	v_exp_f32_e32 v142, v142
	v_exp_f32_e32 v143, v143
	v_pk_add_f32 v[140:141], v[140:141], 1.0 op_sel_hi:[1,0]
	v_pk_add_f32 v[142:143], v[142:143], 1.0 op_sel_hi:[1,0]
	v_rcp_f32_e32 v140, v140
	v_rcp_f32_e32 v141, v141
	v_rcp_f32_e32 v142, v142
	v_rcp_f32_e32 v143, v143
	v_pk_mul_f32 v[44:45], v[44:45], v[140:141]
	v_pk_mul_f32 v[46:47], v[46:47], v[142:143]
	v_pk_mul_f32 v[44:45], v[44:45], v[40:41]
	v_pk_mul_f32 v[46:47], v[46:47], v[42:43]
	v_pk_mul_f32 v[36:37], v[36:37], v[160:161] op_sel_hi:[1,0]
	v_pk_mul_f32 v[32:33], v[32:33], v[160:161] op_sel_hi:[1,0]
	v_pk_mul_f32 v[38:39], v[38:39], v[160:161] op_sel_hi:[1,0]
	v_pk_mul_f32 v[34:35], v[34:35], v[160:161] op_sel_hi:[1,0]
	v_pk_mul_f32 v[140:141], v[36:37], s[2:3] op_sel_hi:[1,0]
	v_pk_mul_f32 v[142:143], v[38:39], s[2:3] op_sel_hi:[1,0]
	v_exp_f32_e32 v140, v140
	v_exp_f32_e32 v141, v141
	v_exp_f32_e32 v142, v142
	v_exp_f32_e32 v143, v143
	v_pk_add_f32 v[140:141], v[140:141], 1.0 op_sel_hi:[1,0]
	v_pk_add_f32 v[142:143], v[142:143], 1.0 op_sel_hi:[1,0]
	v_rcp_f32_e32 v140, v140
	v_rcp_f32_e32 v141, v141
	v_rcp_f32_e32 v142, v142
	v_rcp_f32_e32 v143, v143
	v_pk_mul_f32 v[36:37], v[36:37], v[140:141]
	v_pk_mul_f32 v[38:39], v[38:39], v[142:143]
	v_pk_mul_f32 v[36:37], v[36:37], v[32:33]
	v_pk_mul_f32 v[38:39], v[38:39], v[34:35]
	v_cvt_pk_bf16_f32 v44, v44, v45
	v_cvt_pk_bf16_f32 v45, v46, v47
	v_cvt_pk_bf16_f32 v46, v36, v37
	v_cvt_pk_bf16_f32 v47, v38, v39
	v_add_u32_e32 v149, 0xc6000, v171
	global_store_dwordx4 v149, v[44:47], s[10:11] sc1
	v_pk_mul_f32 v[28:29], v[28:29], v[144:145] op_sel_hi:[1,0]
	v_pk_mul_f32 v[24:25], v[24:25], v[144:145] op_sel_hi:[1,0]
	v_pk_mul_f32 v[30:31], v[30:31], v[144:145] op_sel_hi:[1,0]
	v_pk_mul_f32 v[26:27], v[26:27], v[144:145] op_sel_hi:[1,0]
	v_pk_mul_f32 v[140:141], v[28:29], s[2:3] op_sel_hi:[1,0]
	v_pk_mul_f32 v[142:143], v[30:31], s[2:3] op_sel_hi:[1,0]
	v_exp_f32_e32 v140, v140
	v_exp_f32_e32 v141, v141
	v_exp_f32_e32 v142, v142
	v_exp_f32_e32 v143, v143
	v_pk_add_f32 v[140:141], v[140:141], 1.0 op_sel_hi:[1,0]
	v_pk_add_f32 v[142:143], v[142:143], 1.0 op_sel_hi:[1,0]
	v_rcp_f32_e32 v140, v140
	v_rcp_f32_e32 v141, v141
	v_rcp_f32_e32 v142, v142
	v_rcp_f32_e32 v143, v143
	v_pk_mul_f32 v[28:29], v[28:29], v[140:141]
	v_pk_mul_f32 v[30:31], v[30:31], v[142:143]
	v_pk_mul_f32 v[28:29], v[28:29], v[24:25]
	v_pk_mul_f32 v[30:31], v[30:31], v[26:27]
	v_pk_mul_f32 v[20:21], v[20:21], v[144:145] op_sel_hi:[1,0]
	v_pk_mul_f32 v[16:17], v[16:17], v[144:145] op_sel_hi:[1,0]
	v_pk_mul_f32 v[22:23], v[22:23], v[144:145] op_sel_hi:[1,0]
	v_pk_mul_f32 v[18:19], v[18:19], v[144:145] op_sel_hi:[1,0]
	v_pk_mul_f32 v[140:141], v[20:21], s[2:3] op_sel_hi:[1,0]
	v_pk_mul_f32 v[142:143], v[22:23], s[2:3] op_sel_hi:[1,0]
	v_exp_f32_e32 v140, v140
	v_exp_f32_e32 v141, v141
	v_exp_f32_e32 v142, v142
	v_exp_f32_e32 v143, v143
	v_pk_add_f32 v[140:141], v[140:141], 1.0 op_sel_hi:[1,0]
	v_pk_add_f32 v[142:143], v[142:143], 1.0 op_sel_hi:[1,0]
	v_rcp_f32_e32 v140, v140
	v_rcp_f32_e32 v141, v141
	v_rcp_f32_e32 v142, v142
	v_rcp_f32_e32 v143, v143
	v_pk_mul_f32 v[20:21], v[20:21], v[140:141]
	v_pk_mul_f32 v[22:23], v[22:23], v[142:143]
	v_pk_mul_f32 v[20:21], v[20:21], v[16:17]
	v_pk_mul_f32 v[22:23], v[22:23], v[18:19]
	v_cvt_pk_bf16_f32 v28, v28, v29
	v_cvt_pk_bf16_f32 v29, v30, v31
	v_cvt_pk_bf16_f32 v30, v20, v21
	v_cvt_pk_bf16_f32 v31, v22, v23
	v_add_u32_e32 v149, 0xdc000, v171
	global_store_dwordx4 v149, v[28:31], s[10:11] sc1
	v_pk_mul_f32 v[12:13], v[12:13], v[174:175] op_sel_hi:[1,0]
	v_pk_mul_f32 v[8:9], v[8:9], v[174:175] op_sel_hi:[1,0]
	v_pk_mul_f32 v[14:15], v[14:15], v[174:175] op_sel_hi:[1,0]
	v_pk_mul_f32 v[10:11], v[10:11], v[174:175] op_sel_hi:[1,0]
	v_pk_mul_f32 v[140:141], v[12:13], s[2:3] op_sel_hi:[1,0]
	v_pk_mul_f32 v[142:143], v[14:15], s[2:3] op_sel_hi:[1,0]
	v_exp_f32_e32 v140, v140
	v_exp_f32_e32 v141, v141
	v_exp_f32_e32 v142, v142
	v_exp_f32_e32 v143, v143
	v_pk_add_f32 v[140:141], v[140:141], 1.0 op_sel_hi:[1,0]
	v_pk_add_f32 v[142:143], v[142:143], 1.0 op_sel_hi:[1,0]
	v_rcp_f32_e32 v140, v140
	v_rcp_f32_e32 v141, v141
	v_rcp_f32_e32 v142, v142
	v_rcp_f32_e32 v143, v143
	v_pk_mul_f32 v[12:13], v[12:13], v[140:141]
	v_pk_mul_f32 v[14:15], v[14:15], v[142:143]
	v_pk_mul_f32 v[12:13], v[12:13], v[8:9]
	v_pk_mul_f32 v[14:15], v[14:15], v[10:11]
	v_pk_mul_f32 v[4:5], v[4:5], v[174:175] op_sel_hi:[1,0]
	v_pk_mul_f32 v[0:1], v[0:1], v[174:175] op_sel_hi:[1,0]
	v_pk_mul_f32 v[6:7], v[6:7], v[174:175] op_sel_hi:[1,0]
	v_pk_mul_f32 v[2:3], v[2:3], v[174:175] op_sel_hi:[1,0]
	v_pk_mul_f32 v[140:141], v[4:5], s[2:3] op_sel_hi:[1,0]
	v_pk_mul_f32 v[142:143], v[6:7], s[2:3] op_sel_hi:[1,0]
	v_exp_f32_e32 v140, v140
	v_exp_f32_e32 v141, v141
	v_exp_f32_e32 v142, v142
	v_exp_f32_e32 v143, v143
	v_pk_add_f32 v[140:141], v[140:141], 1.0 op_sel_hi:[1,0]
	v_pk_add_f32 v[142:143], v[142:143], 1.0 op_sel_hi:[1,0]
	v_rcp_f32_e32 v140, v140
	v_rcp_f32_e32 v141, v141
	v_rcp_f32_e32 v142, v142
	v_rcp_f32_e32 v143, v143
	v_pk_mul_f32 v[4:5], v[4:5], v[140:141]
	v_pk_mul_f32 v[6:7], v[6:7], v[142:143]
	v_pk_mul_f32 v[4:5], v[4:5], v[0:1]
	v_pk_mul_f32 v[6:7], v[6:7], v[2:3]
	v_cvt_pk_bf16_f32 v12, v12, v13
	v_cvt_pk_bf16_f32 v13, v14, v15
	v_cvt_pk_bf16_f32 v14, v4, v5
	v_cvt_pk_bf16_f32 v15, v6, v7
	v_add_u32_e32 v149, 0xf2000, v171
	global_store_dwordx4 v149, v[12:15], s[10:11] sc1
	s_mov_b64 s[2:3], -1
	s_andn2_b64 vcc, exec, s[6:7]
	s_cbranch_vccnz .LBB0_515
	s_andn2_b64 vcc, exec, s[8:9]
	s_cbranch_vccnz .LBB0_514
	s_barrier
	s_branch .LBB0_514
